# background weight conversion limited to one wave per workgroup in phases 8 and 10 (less HBM interference with the GEMM/attention still running)
# speedup vs baseline: 1.0073x; 1.0031x over previous
; #define LAS __attribute__((address_space(3)))
; template <bool DRAIN>
; __device__ __forceinline__ void bg_convert(const float* wg1, const float* wu1, const float* wd1, unsigned char* wsw, unsigned* ctl, int done_word, int G, LAS float* scr, int lane) {
;     for (;;) {
;         if (!DRAIN) { if (__hip_atomic_load(ctl + done_word, __ATOMIC_RELAXED, __HIP_MEMORY_SCOPE_AGENT) >= (unsigned)G) break; }
;         int i0 = 0;
;         if (lane == 0) i0 = (int)atomicAdd(ctl + 896, 4u);
;         i0 = __builtin_amdgcn_readfirstlane(i0);
;         if (i0 >= BG_ITEMS) break;
;     ...
;             __syncthreads();
;             if (tid == 0) atomicAdd(ctl + 640, 1u);
;             bg_convert<false>(p.in[I_WG] + (size_t)DM * FFN, p.in[I_WU] + (size_t)DM * FFN, p.in[I_WD] + (size_t)DM * FFN, wsw, ctl, 640, G, scr, lane);
.LBB0_905:
	s_or_b64 exec, exec, s[4:5]
	v_mov_b32_e32 v1, 0
	s_load_dwordx4 s[4:7], s[16:17], 0x78
	s_load_dwordx2 s[10:11], s[16:17], 0x88
	global_load_dword v0, v1, s[14:15] offset:2560 sc1
	s_waitcnt vmcnt(0)
	v_cmp_le_u32_e32 vcc, s34, v0
	s_cbranch_vccnz .LBB0_924
	s_cmp_ge_u32 s33, 1
	s_cbranch_scc1 .LBB0_924
	s_waitcnt lgkmcnt(0)
	s_add_u32 s8, s4, 0x2c00000
	s_addc_u32 s9, s5, 0
	v_and_b32_e32 v2, 7, v156
	s_add_u32 s6, s6, 0x2c00000
	v_lshrrev_b32_e32 v6, 3, v156
	v_lshlrev_b32_e32 v0, 4, v2
	s_mul_i32 s16, s33, 0x2100
	s_addc_u32 s7, s7, 0
	v_or_b32_e32 v11, s16, v0
	v_mul_u32_u24_e32 v12, 0x84, v6
	v_lshl_add_u64 v[4:5], s[14:15], 0, v[0:1]
	s_mov_b64 s[18:19], 0x4c30000
	s_add_u32 s10, s10, 0x2c00000
	v_lshlrev_b32_e32 v26, 2, v2
	v_mul_u32_u24_e32 v10, 0x420, v2
	v_lshl_add_u64 v[2:3], v[4:5], 0, s[18:19]
	v_lshlrev_b32_e32 v0, 2, v6
	s_mov_b64 s[18:19], 0x2030000
	v_add_u32_e32 v11, v11, v12
	s_addc_u32 s11, s11, 0
	s_mov_b32 s17, 0
	v_cmp_eq_u32_e64 s[4:5], 0, v156
	v_add_u32_e32 v7, 8, v6
	v_or_b32_e32 v8, 16, v6
	v_add_u32_e32 v9, 24, v6
	v_add3_u32 v10, s16, v10, v0
	v_lshl_add_u64 v[4:5], v[4:5], 0, s[18:19]
	s_mov_b32 s24, 0x10000
	s_mov_b32 s25, 0x20000
	s_mov_b32 s26, 0x30000
	s_mov_b32 s27, 0x40000
	s_mov_b32 s38, 0x50000
	s_mov_b32 s39, 0x60000
	s_mov_b32 s40, 0x70000
	v_add_u32_e32 v12, 0x420, v11
	v_add_u32_e32 v13, 0x428, v11
	v_add_u32_e32 v14, 0x840, v11
	v_add_u32_e32 v15, 0x848, v11
	v_add_u32_e32 v16, 0xc60, v11
	v_add_u32_e32 v17, 0xc68, v11
	v_add_u32_e32 v18, 0x1080, v11
	v_add_u32_e32 v19, 0x1088, v11
	v_add_u32_e32 v20, 0x14a0, v11
	v_add_u32_e32 v21, 0x14a8, v11
	v_add_u32_e32 v22, 0x18c0, v11
	v_add_u32_e32 v23, 0x18c8, v11
	v_add_u32_e32 v24, 0x1ce0, v11
	v_add_u32_e32 v25, 0x1ce8, v11
	s_movk_i32 s41, 0x2c00
	s_movk_i32 s42, 0x5800
	s_mov_b32 s43, 0x2c000
	s_mov_b32 s44, 0x58000
	s_mov_b32 s45, 0x84000
	s_mov_b32 s46, 0xb0000
	s_mov_b32 s47, 0xdc000
	s_mov_b32 s48, 0x108000
	s_mov_b32 s49, 0x134000
	s_movk_i32 s50, 0x6f
	s_movk_i32 s51, 0x7f
	s_movk_i32 s52, 0xff00
	v_lshlrev_b32_e32 v0, 2, v26
	v_mov_b32_e32 v26, 0x80000
	v_mov_b32_e32 v27, 0x6f
	v_mov_b32_e32 v28, 0x7f
	s_branch .LBB0_909

; #define LAS __attribute__((address_space(3)))
; template <bool DRAIN>
; __device__ __forceinline__ void bg_convert(const float* wg1, const float* wu1, const float* wd1, unsigned char* wsw, unsigned* ctl, int done_word, int G, LAS float* scr, int lane) {
;     for (;;) {
;         if (!DRAIN) { if (__hip_atomic_load(ctl + done_word, __ATOMIC_RELAXED, __HIP_MEMORY_SCOPE_AGENT) >= (unsigned)G) break; }
;         int i0 = 0;
;         if (lane == 0) i0 = (int)atomicAdd(ctl + 896, 4u);
;         i0 = __builtin_amdgcn_readfirstlane(i0);
;         if (i0 >= BG_ITEMS) break;
;     ...
;             __syncthreads();
;             if (tid == 0) atomicAdd(ctl + 704, 1u);
;             bg_convert<false>(p.in[I_WG] + (size_t)DM * FFN, p.in[I_WU] + (size_t)DM * FFN, p.in[I_WD] + (size_t)DM * FFN, wsw, ctl, 704, G, scr, lane);
.LBB0_1159:
	s_or_b64 exec, exec, s[6:7]
	v_mov_b32_e32 v1, 0
	s_load_dwordx4 s[4:7], s[42:43], 0x78
	s_load_dwordx2 s[10:11], s[42:43], 0x88
	global_load_dword v0, v1, s[40:41] offset:2816 sc1
	s_waitcnt vmcnt(0)
	v_cmp_le_u32_e32 vcc, s34, v0
	s_cbranch_vccnz .LBB0_1178
	s_cmp_ge_u32 s33, 1
	s_cbranch_scc1 .LBB0_1178
	s_waitcnt lgkmcnt(0)
	s_add_u32 s8, s4, 0x2c00000
	s_addc_u32 s9, s5, 0
	v_and_b32_e32 v2, 7, v183
	s_add_u32 s6, s6, 0x2c00000
	v_lshrrev_b32_e32 v6, 3, v241
	v_lshlrev_b32_e32 v0, 4, v2
	s_mul_i32 s14, s33, 0x2100
	s_addc_u32 s7, s7, 0
	v_or_b32_e32 v11, s14, v0
	v_mul_u32_u24_e32 v12, 0x84, v6
	s_movk_i32 s12, 0x420
	v_mov_b32_e32 v3, s14
	v_lshl_add_u64 v[4:5], s[40:41], 0, v[0:1]
	s_mov_b64 s[14:15], 0x4c30000
	s_add_u32 s10, s10, 0x2c00000
	v_lshlrev_b32_e32 v26, 2, v2
	v_mad_u32_u24 v10, v2, s12, v3
	v_lshl_add_u64 v[2:3], v[4:5], 0, s[14:15]
	s_mov_b64 s[14:15], 0x2030000
	v_add_u32_e32 v11, v11, v12
	s_addc_u32 s11, s11, 0
	s_mov_b32 s13, 0
	v_cmp_eq_u32_e64 s[4:5], 0, v241
	v_or_b32_e32 v7, 8, v6
	v_or_b32_e32 v8, 16, v6
	v_or_b32_e32 v9, 24, v6
	v_lshl_or_b32 v10, v6, 2, v10
	v_lshl_add_u64 v[4:5], v[4:5], 0, s[14:15]
	s_mov_b32 s20, 0x10000
	s_mov_b32 s21, 0x20000
	s_mov_b32 s22, 0x30000
	s_mov_b32 s23, 0x40000
	s_mov_b32 s24, 0x50000
	s_mov_b32 s25, 0x60000
	s_mov_b32 s26, 0x70000
	v_add_u32_e32 v12, 0x420, v11
	v_add_u32_e32 v13, 0x428, v11
	v_add_u32_e32 v14, 0x840, v11
	v_add_u32_e32 v15, 0x848, v11
	v_add_u32_e32 v16, 0xc60, v11
	v_add_u32_e32 v17, 0xc68, v11
	v_add_u32_e32 v18, 0x1080, v11
	v_add_u32_e32 v19, 0x1088, v11
	v_add_u32_e32 v20, 0x14a0, v11
	v_add_u32_e32 v21, 0x14a8, v11
	v_add_u32_e32 v22, 0x18c0, v11
	v_add_u32_e32 v23, 0x18c8, v11
	v_add_u32_e32 v24, 0x1ce0, v11
	v_add_u32_e32 v25, 0x1ce8, v11
	s_mov_b32 s27, 0x2c000
	s_mov_b32 s42, 0x58000
	s_mov_b32 s43, 0x84000
	s_mov_b32 s44, 0xb0000
	s_mov_b32 s45, 0xdc000
	s_mov_b32 s46, 0x108000
	s_mov_b32 s47, 0x134000
	s_mov_b32 s48, 0x80000
	v_lshlrev_b32_e32 v0, 2, v26
	s_branch .LBB0_1163
